# attention phases (k1, k3): one static s_setprio 1 for waves 0-3 (the other half than v64) at phase entry, reset at phase end
# baseline (speedup 1.0000x reference)
; __global__ void __launch_bounds__(512, 2) mega_fwd(Args ka) {
;     ...
;             if (k == 1) {
;                 for (int rep = 0; rep < ((PROBE_SUB & 1) ? 2 : 1); ++rep) { asm volatile("" : "+v"(tid), "+s"(bid)); phase_compress_mfma(a, l, (unsigned char*)ldsf, tid, tid & 63, __builtin_amdgcn_readfirstlane(tid >> 6), bid, nblk); }
;                 for (int rep = 0; rep < ((PROBE_SUB & 2) ? 2 : 1); ++rep) { asm volatile("" : "+v"(tid), "+s"(bid)); phase_dilated_mfma(a, (unsigned char*)ldsf, tid, tid & 63, __builtin_amdgcn_readfirstlane(tid >> 6), bid, nblk); }
;                 for (int rep = 0; rep < ((PROBE_SUB & 4) ? 2 : 1); ++rep) { asm volatile("" : "+v"(tid), "+s"(bid)); phase_diff_mfma(a, l, (unsigned char*)ldsf, tid, tid & 63, __builtin_amdgcn_readfirstlane(tid >> 6), bid, nblk); } }
;             else if (k == 3) { phase_dil_combine(a, lane, gw, ngw); phase_nsa_mfma(a, (unsigned char*)ldsf, tid, lane, wave, bid, nblk); }
.LBB0_101:
	s_andn2_b64 vcc, exec, s[0:1]
	s_cbranch_vccnz .LBB0_384
	s_mov_b64 s[8:9], s[80:81]
	v_writelane_b32 v253, s73, 30
	s_mov_b32 s10, s82
	v_writelane_b32 v253, s8, 31
	s_add_i32 s73, s20, 0
	s_cmp_lt_i32 s27, 3
	v_writelane_b32 v253, s9, 32
	v_writelane_b32 v253, s10, 33
	v_writelane_b32 v253, s11, 34
	v_writelane_b32 v253, s30, 35
	s_mov_b64 s[0:1], -1
	s_nop 0
	v_writelane_b32 v253, s31, 36
	v_writelane_b32 v253, s58, 37
	s_cbranch_scc1 .LBB0_219
	s_cmp_eq_u32 s27, 3
	s_cbranch_scc0 .LBB0_218
	v_readfirstlane_b32 s0, v210
	s_nop 3
	s_cmp_lt_u32 s0, 0x100
	s_cbranch_scc0 .Lprio_skip_k3
	s_setprio 1

; __global__ void __launch_bounds__(512, 2) mega_fwd(Args ka) {
;     ...
;             if (k == 1) {
;                 for (int rep = 0; rep < ((PROBE_SUB & 1) ? 2 : 1); ++rep) { asm volatile("" : "+v"(tid), "+s"(bid)); phase_compress_mfma(a, l, (unsigned char*)ldsf, tid, tid & 63, __builtin_amdgcn_readfirstlane(tid >> 6), bid, nblk); }
;                 for (int rep = 0; rep < ((PROBE_SUB & 2) ? 2 : 1); ++rep) { asm volatile("" : "+v"(tid), "+s"(bid)); phase_dilated_mfma(a, (unsigned char*)ldsf, tid, tid & 63, __builtin_amdgcn_readfirstlane(tid >> 6), bid, nblk); }
;                 for (int rep = 0; rep < ((PROBE_SUB & 4) ? 2 : 1); ++rep) { asm volatile("" : "+v"(tid), "+s"(bid)); phase_diff_mfma(a, l, (unsigned char*)ldsf, tid, tid & 63, __builtin_amdgcn_readfirstlane(tid >> 6), bid, nblk); } }
.LBB0_219:
	s_andn2_b64 vcc, exec, s[0:1]
	s_cbranch_vccnz .LBB0_383
	s_cmp_lg_u32 s27, 1
	s_cbranch_scc1 .LBB0_383
	v_readfirstlane_b32 s0, v210
	s_nop 3
	s_cmp_lt_u32 s0, 0x100
	s_cbranch_scc0 .Lprio_skip_k1
	s_setprio 1
